# bundle 2: adds static priority for waves 4-7 in the attention part, scalar (unpacked) softmax ops in attnA, 16-byte hyena conv epilogue through LDS
# baseline (speedup 1.0000x reference)
; __device__ __forceinline__ unsigned pk2(float lo, float hi) { unsigned r; asm("v_cvt_pk_bf16_f32 %0, %1, %2" : "=v"(r) : "v"(lo), "v"(hi)); return r; }
; __device__ __forceinline__ float bf2f(bf16_t b) { return __uint_as_float(((unsigned)b) << 16); }
; template <int EPI>
; __device__ __forceinline__ void hy_conv(const Args& a, int L, int c, const bf16_t* U, LAS unsigned char* lds) {
;     ...
;             for (int k = 0; k < 4; ++k)
; #pragma unroll
;                 for (int tt = 0; tt < 4; ++tt) acc[tt] = __builtin_amdgcn_mfma_f32_32x32x16_bf16(ac[k], bfr[k - 2 * tt + 6], acc[tt], 0, 0, 0);
;         }
; #pragma unroll
;         for (int tt = 0; tt < 4; ++tt)
; #pragma unroll
;             for (int i = 0; i < 16; ++i) {
;                 const int bb = (i & 3) + 8 * (i >> 2) + 4 * h, t = 32 * (tb + tt) + n;
;                 const size_t tok = (size_t)bb * SEQ + t;
;                 if (EPI == 0) {
;                     const float v = bf2f(UC[(size_t)c * MTOK + tok]), x1 = bf2f(UC[((size_t)256 + c) * MTOK + tok]);
;                     const float z = x1 * (acc[tt][i] + dbias * v);
;                     Z[tok] = (bf16_t)(pk2(z, 0.f) & 0xffffu);
;                 } else {
;                     const float zz = bf2f(Z[tok]), x2 = bf2f(UC[((size_t)512 + c) * MTOK + tok]);
;                     const float o = x2 * (acc[tt][i] + dbias * zz);
;                     MIX[tok * DM + 384 + c] = (bf16_t)(pk2(o, 0.f) & 0xffffu);
;                 }
;             }
.Lhc0_last:
	v_mfma_f32_32x32x16_bf16 v[48:63], v[80:83], v[196:199], v[48:63]
	v_mfma_f32_32x32x16_bf16 v[32:47], v[80:83], v[188:191], v[32:47]
	v_mfma_f32_32x32x16_bf16 v[16:31], v[80:83], v[144:147], v[16:31]
	v_mfma_f32_32x32x16_bf16 v[0:15], v[80:83], v[136:139], v[0:15]
	v_mfma_f32_32x32x16_bf16 v[48:63], v[84:87], v[200:203], v[48:63]
	v_mfma_f32_32x32x16_bf16 v[32:47], v[84:87], v[192:195], v[32:47]
	v_mfma_f32_32x32x16_bf16 v[16:31], v[84:87], v[148:151], v[16:31]
	v_mfma_f32_32x32x16_bf16 v[0:15], v[84:87], v[140:143], v[0:15]
	v_mfma_f32_32x32x16_bf16 v[48:63], v[88:91], v[204:207], v[48:63]
	v_mfma_f32_32x32x16_bf16 v[32:47], v[88:91], v[196:199], v[32:47]
	v_mfma_f32_32x32x16_bf16 v[16:31], v[88:91], v[188:191], v[16:31]
	v_mfma_f32_32x32x16_bf16 v[0:15], v[88:91], v[144:147], v[0:15]
	v_mfma_f32_32x32x16_bf16 v[48:63], v[92:95], v[216:219], v[48:63]
	v_mfma_f32_32x32x16_bf16 v[32:47], v[92:95], v[200:203], v[32:47]
	v_mfma_f32_32x32x16_bf16 v[16:31], v[92:95], v[192:195], v[16:31]
	v_mfma_f32_32x32x16_bf16 v[0:15], v[92:95], v[148:151], v[0:15]
	v_mov_b32_e32 v213, v215
	s_add_u32 s26, s26, 1
	s_lshr_b32 s30, s26, 3
	s_sub_u32 s30, s30, 1
	s_lshl_b32 s30, s30, 2
	v_and_b32_e32 v138, 63, v225
	v_lshrrev_b32_e32 v142, 6, v225
	v_lshrrev_b32_e32 v140, 2, v138
	v_and_b32_e32 v141, 3, v138
	v_lshlrev_b32_e32 v143, 4, v141
	v_lshl_or_b32 v143, v140, 12, v143
	v_lshl_or_b32 v143, v142, 9, v143
	s_lshl_b32 s28, s30, 6
	v_or_b32_e32 v143, s28, v143
	v_add_u32_e32 v144, 0x10000, v143
	v_and_b32_e32 v139, 31, v138
	v_lshrrev_b32_e32 v137, 5, v138
	v_lshlrev_b32_e32 v145, 2, v139
	v_lshl_or_b32 v145, v137, 9, v145
	v_lshl_or_b32 v145, v142, 11, v145
	v_add_u32_e32 v146, 0x24000, v145
	v_add_u32_e32 v145, 0x10200, v145
	v_lshlrev_b32_e32 v147, 5, v141
	v_lshl_or_b32 v147, v140, 7, v147
	v_lshl_or_b32 v147, v142, 11, v147
	v_add_u32_e32 v148, 0x24000, v147
	v_add_u32_e32 v147, 0x10200, v147
	global_load_dwordx4 v[64:67], v143, s[22:23] offset:0
	global_load_dwordx4 v[68:71], v143, s[24:25] offset:0
	global_load_dwordx4 v[72:75], v144, s[22:23] offset:0
	global_load_dwordx4 v[76:79], v144, s[24:25] offset:0
	global_load_dwordx4 v[80:83], v143, s[22:23] offset:64
	global_load_dwordx4 v[84:87], v143, s[24:25] offset:64
	global_load_dwordx4 v[88:91], v144, s[22:23] offset:64
	global_load_dwordx4 v[92:95], v144, s[24:25] offset:64
	global_load_dwordx4 v[96:99], v143, s[22:23] offset:128
	global_load_dwordx4 v[100:103], v143, s[24:25] offset:128
	global_load_dwordx4 v[104:107], v144, s[22:23] offset:128
	global_load_dwordx4 v[108:111], v144, s[24:25] offset:128
	global_load_dwordx4 v[112:115], v143, s[22:23] offset:192
	global_load_dwordx4 v[116:119], v143, s[24:25] offset:192
	global_load_dwordx4 v[120:123], v144, s[22:23] offset:192
	global_load_dwordx4 v[124:127], v144, s[24:25] offset:192
	ds_write_b32 v145, v48 offset:0
	ds_write_b32 v145, v49 offset:128
	ds_write_b32 v145, v50 offset:256
	ds_write_b32 v145, v51 offset:384
	ds_write_b32 v145, v52 offset:1024
	ds_write_b32 v145, v53 offset:1152
	ds_write_b32 v145, v54 offset:1280
	ds_write_b32 v145, v55 offset:1408
	s_waitcnt lgkmcnt(0)
	ds_read_b128 v[128:131], v147
	ds_read_b128 v[132:135], v147 offset:16
	ds_write_b32 v146, v56 offset:0
	ds_write_b32 v146, v57 offset:128
	ds_write_b32 v146, v58 offset:256
	ds_write_b32 v146, v59 offset:384
	ds_write_b32 v146, v60 offset:1024
	ds_write_b32 v146, v61 offset:1152
	ds_write_b32 v146, v62 offset:1280
	ds_write_b32 v146, v63 offset:1408
	s_waitcnt lgkmcnt(8)
	s_waitcnt vmcnt(14)
	v_lshlrev_b32_e32 v136, 16, v64
	v_lshlrev_b32_e32 v137, 16, v68
	v_fmac_f32_e32 v128, v184, v136
	v_mul_f32_e32 v128, v128, v137
	v_and_b32_e32 v136, 0xffff0000, v64
	v_and_b32_e32 v137, 0xffff0000, v68
	v_fmac_f32_e32 v129, v184, v136
	v_mul_f32_e32 v129, v129, v137
	v_lshlrev_b32_e32 v136, 16, v65
	v_lshlrev_b32_e32 v137, 16, v69
	v_fmac_f32_e32 v130, v184, v136
	v_mul_f32_e32 v130, v130, v137
	v_and_b32_e32 v136, 0xffff0000, v65
	v_and_b32_e32 v137, 0xffff0000, v69
	v_fmac_f32_e32 v131, v184, v136
	v_mul_f32_e32 v131, v131, v137
	v_lshlrev_b32_e32 v136, 16, v66
	v_lshlrev_b32_e32 v137, 16, v70
	v_fmac_f32_e32 v132, v184, v136
	v_mul_f32_e32 v132, v132, v137
	v_and_b32_e32 v136, 0xffff0000, v66
	v_and_b32_e32 v137, 0xffff0000, v70
	v_fmac_f32_e32 v133, v184, v136
	v_mul_f32_e32 v133, v133, v137
	v_lshlrev_b32_e32 v136, 16, v67
	v_lshlrev_b32_e32 v137, 16, v71
	v_fmac_f32_e32 v134, v184, v136
	v_mul_f32_e32 v134, v134, v137
	v_and_b32_e32 v136, 0xffff0000, v67
	v_and_b32_e32 v137, 0xffff0000, v71
	v_fmac_f32_e32 v135, v184, v136
	v_mul_f32_e32 v135, v135, v137
	v_cvt_pk_bf16_f32 v64, v128, v129
	v_cvt_pk_bf16_f32 v65, v130, v131
	v_cvt_pk_bf16_f32 v66, v132, v133
	v_cvt_pk_bf16_f32 v67, v134, v135
	global_store_dwordx4 v143, v[64:67], s[20:21] offset:0
	s_waitcnt lgkmcnt(0)
	ds_read_b128 v[128:131], v148
	ds_read_b128 v[132:135], v148 offset:16
	ds_write_b32 v145, v32 offset:0
	ds_write_b32 v145, v33 offset:128
	ds_write_b32 v145, v34 offset:256
	ds_write_b32 v145, v35 offset:384
	ds_write_b32 v145, v36 offset:1024
	ds_write_b32 v145, v37 offset:1152
	ds_write_b32 v145, v38 offset:1280
	ds_write_b32 v145, v39 offset:1408
	s_waitcnt lgkmcnt(8)
	s_waitcnt vmcnt(13)
; __device__ __forceinline__ unsigned pk2(float lo, float hi) { unsigned r; asm("v_cvt_pk_bf16_f32 %0, %1, %2" : "=v"(r) : "v"(lo), "v"(hi)); return r; }
; __device__ __forceinline__ float bf2f(bf16_t b) { return __uint_as_float(((unsigned)b) << 16); }
; template <int EPI>
; __device__ __forceinline__ void hy_conv(const Args& a, int L, int c, const bf16_t* U, LAS unsigned char* lds) {
;     ...
;         for (int tt = 0; tt < 4; ++tt)
; #pragma unroll
;             for (int i = 0; i < 16; ++i) {
;                 const int bb = (i & 3) + 8 * (i >> 2) + 4 * h, t = 32 * (tb + tt) + n;
;                 const size_t tok = (size_t)bb * SEQ + t;
;                 if (EPI == 0) {
;                     const float v = bf2f(UC[(size_t)c * MTOK + tok]), x1 = bf2f(UC[((size_t)256 + c) * MTOK + tok]);
;                     const float z = x1 * (acc[tt][i] + dbias * v);
;                     Z[tok] = (bf16_t)(pk2(z, 0.f) & 0xffffu);
	v_lshlrev_b32_e32 v136, 16, v72
	v_lshlrev_b32_e32 v137, 16, v76
	v_fmac_f32_e32 v128, v184, v136
	v_mul_f32_e32 v128, v128, v137
	v_and_b32_e32 v136, 0xffff0000, v72
	v_and_b32_e32 v137, 0xffff0000, v76
	v_fmac_f32_e32 v129, v184, v136
	v_mul_f32_e32 v129, v129, v137
	v_lshlrev_b32_e32 v136, 16, v73
	v_lshlrev_b32_e32 v137, 16, v77
	v_fmac_f32_e32 v130, v184, v136
	v_mul_f32_e32 v130, v130, v137
	v_and_b32_e32 v136, 0xffff0000, v73
	v_and_b32_e32 v137, 0xffff0000, v77
	v_fmac_f32_e32 v131, v184, v136
	v_mul_f32_e32 v131, v131, v137
	v_lshlrev_b32_e32 v136, 16, v74
	v_lshlrev_b32_e32 v137, 16, v78
	v_fmac_f32_e32 v132, v184, v136
	v_mul_f32_e32 v132, v132, v137
	v_and_b32_e32 v136, 0xffff0000, v74
	v_and_b32_e32 v137, 0xffff0000, v78
	v_fmac_f32_e32 v133, v184, v136
	v_mul_f32_e32 v133, v133, v137
	v_lshlrev_b32_e32 v136, 16, v75
	v_lshlrev_b32_e32 v137, 16, v79
	v_fmac_f32_e32 v134, v184, v136
	v_mul_f32_e32 v134, v134, v137
	v_and_b32_e32 v136, 0xffff0000, v75
	v_and_b32_e32 v137, 0xffff0000, v79
	v_fmac_f32_e32 v135, v184, v136
	v_mul_f32_e32 v135, v135, v137
	v_cvt_pk_bf16_f32 v72, v128, v129
	v_cvt_pk_bf16_f32 v73, v130, v131
	v_cvt_pk_bf16_f32 v74, v132, v133
	v_cvt_pk_bf16_f32 v75, v134, v135
	global_store_dwordx4 v144, v[72:75], s[20:21] offset:0
	s_waitcnt lgkmcnt(0)
	ds_read_b128 v[128:131], v147
	ds_read_b128 v[132:135], v147 offset:16
	ds_write_b32 v146, v40 offset:0
	ds_write_b32 v146, v41 offset:128
	ds_write_b32 v146, v42 offset:256
	ds_write_b32 v146, v43 offset:384
	ds_write_b32 v146, v44 offset:1024
	ds_write_b32 v146, v45 offset:1152
	ds_write_b32 v146, v46 offset:1280
	ds_write_b32 v146, v47 offset:1408
	s_waitcnt lgkmcnt(8)
	s_waitcnt vmcnt(12)
	v_lshlrev_b32_e32 v136, 16, v80
	v_lshlrev_b32_e32 v137, 16, v84
	v_fmac_f32_e32 v128, v184, v136
	v_mul_f32_e32 v128, v128, v137
	v_and_b32_e32 v136, 0xffff0000, v80
	v_and_b32_e32 v137, 0xffff0000, v84
	v_fmac_f32_e32 v129, v184, v136
	v_mul_f32_e32 v129, v129, v137
	v_lshlrev_b32_e32 v136, 16, v81
	v_lshlrev_b32_e32 v137, 16, v85
	v_fmac_f32_e32 v130, v184, v136
	v_mul_f32_e32 v130, v130, v137
	v_and_b32_e32 v136, 0xffff0000, v81
	v_and_b32_e32 v137, 0xffff0000, v85
	v_fmac_f32_e32 v131, v184, v136
	v_mul_f32_e32 v131, v131, v137
	v_lshlrev_b32_e32 v136, 16, v82
	v_lshlrev_b32_e32 v137, 16, v86
	v_fmac_f32_e32 v132, v184, v136
	v_mul_f32_e32 v132, v132, v137
	v_and_b32_e32 v136, 0xffff0000, v82
	v_and_b32_e32 v137, 0xffff0000, v86
	v_fmac_f32_e32 v133, v184, v136
	v_mul_f32_e32 v133, v133, v137
	v_lshlrev_b32_e32 v136, 16, v83
	v_lshlrev_b32_e32 v137, 16, v87
	v_fmac_f32_e32 v134, v184, v136
	v_mul_f32_e32 v134, v134, v137
	v_and_b32_e32 v136, 0xffff0000, v83
	v_and_b32_e32 v137, 0xffff0000, v87
	v_fmac_f32_e32 v135, v184, v136
	v_mul_f32_e32 v135, v135, v137
	v_cvt_pk_bf16_f32 v80, v128, v129
	v_cvt_pk_bf16_f32 v81, v130, v131
	v_cvt_pk_bf16_f32 v82, v132, v133
	v_cvt_pk_bf16_f32 v83, v134, v135
	global_store_dwordx4 v143, v[80:83], s[20:21] offset:64
	s_waitcnt lgkmcnt(0)
	ds_read_b128 v[128:131], v148
	ds_read_b128 v[132:135], v148 offset:16
	ds_write_b32 v145, v16 offset:0
	ds_write_b32 v145, v17 offset:128
	ds_write_b32 v145, v18 offset:256
	ds_write_b32 v145, v19 offset:384
	ds_write_b32 v145, v20 offset:1024
	ds_write_b32 v145, v21 offset:1152
	ds_write_b32 v145, v22 offset:1280
	ds_write_b32 v145, v23 offset:1408
	s_waitcnt lgkmcnt(8)
	s_waitcnt vmcnt(11)
	v_lshlrev_b32_e32 v136, 16, v88
	v_lshlrev_b32_e32 v137, 16, v92
	v_fmac_f32_e32 v128, v184, v136
	v_mul_f32_e32 v128, v128, v137
	v_and_b32_e32 v136, 0xffff0000, v88
	v_and_b32_e32 v137, 0xffff0000, v92
	v_fmac_f32_e32 v129, v184, v136
	v_mul_f32_e32 v129, v129, v137
	v_lshlrev_b32_e32 v136, 16, v89
	v_lshlrev_b32_e32 v137, 16, v93
	v_fmac_f32_e32 v130, v184, v136
	v_mul_f32_e32 v130, v130, v137
	v_and_b32_e32 v136, 0xffff0000, v89
	v_and_b32_e32 v137, 0xffff0000, v93
	v_fmac_f32_e32 v131, v184, v136
	v_mul_f32_e32 v131, v131, v137
	v_lshlrev_b32_e32 v136, 16, v90
	v_lshlrev_b32_e32 v137, 16, v94
	v_fmac_f32_e32 v132, v184, v136
	v_mul_f32_e32 v132, v132, v137
	v_and_b32_e32 v136, 0xffff0000, v90
	v_and_b32_e32 v137, 0xffff0000, v94
	v_fmac_f32_e32 v133, v184, v136
	v_mul_f32_e32 v133, v133, v137
	v_lshlrev_b32_e32 v136, 16, v91
	v_lshlrev_b32_e32 v137, 16, v95
	v_fmac_f32_e32 v134, v184, v136
	v_mul_f32_e32 v134, v134, v137
	v_and_b32_e32 v136, 0xffff0000, v91
	v_and_b32_e32 v137, 0xffff0000, v95
	v_fmac_f32_e32 v135, v184, v136
	v_mul_f32_e32 v135, v135, v137
	v_cvt_pk_bf16_f32 v88, v128, v129
	v_cvt_pk_bf16_f32 v89, v130, v131
	v_cvt_pk_bf16_f32 v90, v132, v133
	v_cvt_pk_bf16_f32 v91, v134, v135
	global_store_dwordx4 v144, v[88:91], s[20:21] offset:64
	s_waitcnt lgkmcnt(0)
	ds_read_b128 v[128:131], v147
	ds_read_b128 v[132:135], v147 offset:16
	ds_write_b32 v146, v24 offset:0
	ds_write_b32 v146, v25 offset:128
	ds_write_b32 v146, v26 offset:256
	ds_write_b32 v146, v27 offset:384
	ds_write_b32 v146, v28 offset:1024
	ds_write_b32 v146, v29 offset:1152
	ds_write_b32 v146, v30 offset:1280
	ds_write_b32 v146, v31 offset:1408
	s_waitcnt lgkmcnt(8)
	s_waitcnt vmcnt(10)
; __device__ __forceinline__ unsigned pk2(float lo, float hi) { unsigned r; asm("v_cvt_pk_bf16_f32 %0, %1, %2" : "=v"(r) : "v"(lo), "v"(hi)); return r; }
; __device__ __forceinline__ float bf2f(bf16_t b) { return __uint_as_float(((unsigned)b) << 16); }
; template <int EPI>
; __device__ __forceinline__ void hy_conv(const Args& a, int L, int c, const bf16_t* U, LAS unsigned char* lds) {
;     ...
;         for (int tt = 0; tt < 4; ++tt)
; #pragma unroll
;             for (int i = 0; i < 16; ++i) {
;                 const int bb = (i & 3) + 8 * (i >> 2) + 4 * h, t = 32 * (tb + tt) + n;
;                 const size_t tok = (size_t)bb * SEQ + t;
;                 if (EPI == 0) {
;                     const float v = bf2f(UC[(size_t)c * MTOK + tok]), x1 = bf2f(UC[((size_t)256 + c) * MTOK + tok]);
;                     const float z = x1 * (acc[tt][i] + dbias * v);
;                     Z[tok] = (bf16_t)(pk2(z, 0.f) & 0xffffu);
	v_lshlrev_b32_e32 v136, 16, v96
	v_lshlrev_b32_e32 v137, 16, v100
	v_fmac_f32_e32 v128, v184, v136
	v_mul_f32_e32 v128, v128, v137
	v_and_b32_e32 v136, 0xffff0000, v96
	v_and_b32_e32 v137, 0xffff0000, v100
	v_fmac_f32_e32 v129, v184, v136
	v_mul_f32_e32 v129, v129, v137
	v_lshlrev_b32_e32 v136, 16, v97
	v_lshlrev_b32_e32 v137, 16, v101
	v_fmac_f32_e32 v130, v184, v136
	v_mul_f32_e32 v130, v130, v137
	v_and_b32_e32 v136, 0xffff0000, v97
	v_and_b32_e32 v137, 0xffff0000, v101
	v_fmac_f32_e32 v131, v184, v136
	v_mul_f32_e32 v131, v131, v137
	v_lshlrev_b32_e32 v136, 16, v98
	v_lshlrev_b32_e32 v137, 16, v102
	v_fmac_f32_e32 v132, v184, v136
	v_mul_f32_e32 v132, v132, v137
	v_and_b32_e32 v136, 0xffff0000, v98
	v_and_b32_e32 v137, 0xffff0000, v102
	v_fmac_f32_e32 v133, v184, v136
	v_mul_f32_e32 v133, v133, v137
	v_lshlrev_b32_e32 v136, 16, v99
	v_lshlrev_b32_e32 v137, 16, v103
	v_fmac_f32_e32 v134, v184, v136
	v_mul_f32_e32 v134, v134, v137
	v_and_b32_e32 v136, 0xffff0000, v99
	v_and_b32_e32 v137, 0xffff0000, v103
	v_fmac_f32_e32 v135, v184, v136
	v_mul_f32_e32 v135, v135, v137
	v_cvt_pk_bf16_f32 v96, v128, v129
	v_cvt_pk_bf16_f32 v97, v130, v131
	v_cvt_pk_bf16_f32 v98, v132, v133
	v_cvt_pk_bf16_f32 v99, v134, v135
	global_store_dwordx4 v143, v[96:99], s[20:21] offset:128
	s_waitcnt lgkmcnt(0)
	ds_read_b128 v[128:131], v148
	ds_read_b128 v[132:135], v148 offset:16
	ds_write_b32 v145, v0 offset:0
	ds_write_b32 v145, v1 offset:128
	ds_write_b32 v145, v2 offset:256
	ds_write_b32 v145, v3 offset:384
	ds_write_b32 v145, v4 offset:1024
	ds_write_b32 v145, v5 offset:1152
	ds_write_b32 v145, v6 offset:1280
	ds_write_b32 v145, v7 offset:1408
	s_waitcnt lgkmcnt(8)
	s_waitcnt vmcnt(9)
	v_lshlrev_b32_e32 v136, 16, v104
	v_lshlrev_b32_e32 v137, 16, v108
	v_fmac_f32_e32 v128, v184, v136
	v_mul_f32_e32 v128, v128, v137
	v_and_b32_e32 v136, 0xffff0000, v104
	v_and_b32_e32 v137, 0xffff0000, v108
	v_fmac_f32_e32 v129, v184, v136
	v_mul_f32_e32 v129, v129, v137
	v_lshlrev_b32_e32 v136, 16, v105
	v_lshlrev_b32_e32 v137, 16, v109
	v_fmac_f32_e32 v130, v184, v136
	v_mul_f32_e32 v130, v130, v137
	v_and_b32_e32 v136, 0xffff0000, v105
	v_and_b32_e32 v137, 0xffff0000, v109
	v_fmac_f32_e32 v131, v184, v136
	v_mul_f32_e32 v131, v131, v137
	v_lshlrev_b32_e32 v136, 16, v106
	v_lshlrev_b32_e32 v137, 16, v110
	v_fmac_f32_e32 v132, v184, v136
	v_mul_f32_e32 v132, v132, v137
	v_and_b32_e32 v136, 0xffff0000, v106
	v_and_b32_e32 v137, 0xffff0000, v110
	v_fmac_f32_e32 v133, v184, v136
	v_mul_f32_e32 v133, v133, v137
	v_lshlrev_b32_e32 v136, 16, v107
	v_lshlrev_b32_e32 v137, 16, v111
	v_fmac_f32_e32 v134, v184, v136
	v_mul_f32_e32 v134, v134, v137
	v_and_b32_e32 v136, 0xffff0000, v107
	v_and_b32_e32 v137, 0xffff0000, v111
	v_fmac_f32_e32 v135, v184, v136
	v_mul_f32_e32 v135, v135, v137
	v_cvt_pk_bf16_f32 v104, v128, v129
	v_cvt_pk_bf16_f32 v105, v130, v131
	v_cvt_pk_bf16_f32 v106, v132, v133
	v_cvt_pk_bf16_f32 v107, v134, v135
	global_store_dwordx4 v144, v[104:107], s[20:21] offset:128
	s_waitcnt lgkmcnt(0)
	ds_read_b128 v[128:131], v147
	ds_read_b128 v[132:135], v147 offset:16
	ds_write_b32 v146, v8 offset:0
	ds_write_b32 v146, v9 offset:128
	ds_write_b32 v146, v10 offset:256
	ds_write_b32 v146, v11 offset:384
	ds_write_b32 v146, v12 offset:1024
	ds_write_b32 v146, v13 offset:1152
	ds_write_b32 v146, v14 offset:1280
	ds_write_b32 v146, v15 offset:1408
	s_waitcnt lgkmcnt(8)
	s_waitcnt vmcnt(8)
	v_lshlrev_b32_e32 v136, 16, v112
	v_lshlrev_b32_e32 v137, 16, v116
	v_fmac_f32_e32 v128, v184, v136
	v_mul_f32_e32 v128, v128, v137
	v_and_b32_e32 v136, 0xffff0000, v112
	v_and_b32_e32 v137, 0xffff0000, v116
	v_fmac_f32_e32 v129, v184, v136
	v_mul_f32_e32 v129, v129, v137
	v_lshlrev_b32_e32 v136, 16, v113
	v_lshlrev_b32_e32 v137, 16, v117
	v_fmac_f32_e32 v130, v184, v136
	v_mul_f32_e32 v130, v130, v137
	v_and_b32_e32 v136, 0xffff0000, v113
	v_and_b32_e32 v137, 0xffff0000, v117
	v_fmac_f32_e32 v131, v184, v136
	v_mul_f32_e32 v131, v131, v137
	v_lshlrev_b32_e32 v136, 16, v114
	v_lshlrev_b32_e32 v137, 16, v118
	v_fmac_f32_e32 v132, v184, v136
	v_mul_f32_e32 v132, v132, v137
	v_and_b32_e32 v136, 0xffff0000, v114
	v_and_b32_e32 v137, 0xffff0000, v118
	v_fmac_f32_e32 v133, v184, v136
	v_mul_f32_e32 v133, v133, v137
	v_lshlrev_b32_e32 v136, 16, v115
	v_lshlrev_b32_e32 v137, 16, v119
	v_fmac_f32_e32 v134, v184, v136
	v_mul_f32_e32 v134, v134, v137
	v_and_b32_e32 v136, 0xffff0000, v115
	v_and_b32_e32 v137, 0xffff0000, v119
	v_fmac_f32_e32 v135, v184, v136
	v_mul_f32_e32 v135, v135, v137
	v_cvt_pk_bf16_f32 v112, v128, v129
	v_cvt_pk_bf16_f32 v113, v130, v131
	v_cvt_pk_bf16_f32 v114, v132, v133
	v_cvt_pk_bf16_f32 v115, v134, v135
	global_store_dwordx4 v143, v[112:115], s[20:21] offset:192
	s_waitcnt lgkmcnt(0)
	ds_read_b128 v[128:131], v148
	ds_read_b128 v[132:135], v148 offset:16
	s_waitcnt lgkmcnt(0)
	s_waitcnt vmcnt(7)
	v_lshlrev_b32_e32 v136, 16, v120
	v_lshlrev_b32_e32 v137, 16, v124
	v_fmac_f32_e32 v128, v184, v136
	v_mul_f32_e32 v128, v128, v137
	v_and_b32_e32 v136, 0xffff0000, v120
	v_and_b32_e32 v137, 0xffff0000, v124
	v_fmac_f32_e32 v129, v184, v136
	v_mul_f32_e32 v129, v129, v137
	v_lshlrev_b32_e32 v136, 16, v121
	v_lshlrev_b32_e32 v137, 16, v125
	v_fmac_f32_e32 v130, v184, v136
	v_mul_f32_e32 v130, v130, v137
	v_and_b32_e32 v136, 0xffff0000, v121
	v_and_b32_e32 v137, 0xffff0000, v125
	v_fmac_f32_e32 v131, v184, v136
	v_mul_f32_e32 v131, v131, v137
	v_lshlrev_b32_e32 v136, 16, v122
	v_lshlrev_b32_e32 v137, 16, v126
	v_fmac_f32_e32 v132, v184, v136
	v_mul_f32_e32 v132, v132, v137
	v_and_b32_e32 v136, 0xffff0000, v122
	v_and_b32_e32 v137, 0xffff0000, v126
	v_fmac_f32_e32 v133, v184, v136
	v_mul_f32_e32 v133, v133, v137
	v_lshlrev_b32_e32 v136, 16, v123
	v_lshlrev_b32_e32 v137, 16, v127
	v_fmac_f32_e32 v134, v184, v136
	v_mul_f32_e32 v134, v134, v137
	v_and_b32_e32 v136, 0xffff0000, v123
	v_and_b32_e32 v137, 0xffff0000, v127
	v_fmac_f32_e32 v135, v184, v136
	v_mul_f32_e32 v135, v135, v137
	v_cvt_pk_bf16_f32 v120, v128, v129
	v_cvt_pk_bf16_f32 v121, v130, v131
	v_cvt_pk_bf16_f32 v122, v132, v133
	v_cvt_pk_bf16_f32 v123, v134, v135
	global_store_dwordx4 v144, v[120:123], s[20:21] offset:192
	s_cmp_eq_u32 s26, 16
	s_cbranch_scc1 .Lhc0_done
; template <int EPI>
; __device__ __forceinline__ void hy_conv(const Args& a, int L, int c, const bf16_t* U, LAS unsigned char* lds) {
;     ...
;     for (int blk = 0; blk < 2; ++blk) {
;         const int tb = 8 * wid + 4 * blk;
;         f32x16 acc[4];
; #pragma unroll
;         for (int tt = 0; tt < 4; ++tt)
; #pragma unroll
;             for (int i = 0; i < 16; ++i) acc[tt][i] = 0.f;
;         bf16x8 an[4];
; #pragma unroll
;         for (int k = 0; k < 4; ++k) an[k] = *(const bf16x8*)(urow + 16 * k);
; #pragma unroll 1
	v_mov_b32_e32 v0, 0
	v_mov_b32_e32 v1, 0
	v_mov_b32_e32 v2, 0
	v_mov_b32_e32 v3, 0
	v_mov_b32_e32 v4, 0
	v_mov_b32_e32 v5, 0
	v_mov_b32_e32 v6, 0
	v_mov_b32_e32 v7, 0
	v_mov_b32_e32 v8, 0
	v_mov_b32_e32 v9, 0
	v_mov_b32_e32 v10, 0
	v_mov_b32_e32 v11, 0
	v_mov_b32_e32 v12, 0
	v_mov_b32_e32 v13, 0
	v_mov_b32_e32 v14, 0
	v_mov_b32_e32 v15, 0
	v_mov_b32_e32 v16, 0
	v_mov_b32_e32 v17, 0
	v_mov_b32_e32 v18, 0
	v_mov_b32_e32 v19, 0
	v_mov_b32_e32 v20, 0
	v_mov_b32_e32 v21, 0
	v_mov_b32_e32 v22, 0
	v_mov_b32_e32 v23, 0
	v_mov_b32_e32 v24, 0
	v_mov_b32_e32 v25, 0
	v_mov_b32_e32 v26, 0
	v_mov_b32_e32 v27, 0
	v_mov_b32_e32 v28, 0
	v_mov_b32_e32 v29, 0
	v_mov_b32_e32 v30, 0
	v_mov_b32_e32 v31, 0
	v_mov_b32_e32 v32, 0
	v_mov_b32_e32 v33, 0
	v_mov_b32_e32 v34, 0
	v_mov_b32_e32 v35, 0
	v_mov_b32_e32 v36, 0
	v_mov_b32_e32 v37, 0
	v_mov_b32_e32 v38, 0
	v_mov_b32_e32 v39, 0
	v_mov_b32_e32 v40, 0
	v_mov_b32_e32 v41, 0
	v_mov_b32_e32 v42, 0
	v_mov_b32_e32 v43, 0
	v_mov_b32_e32 v44, 0
	v_mov_b32_e32 v45, 0
	v_mov_b32_e32 v46, 0
	v_mov_b32_e32 v47, 0
	v_mov_b32_e32 v48, 0
	v_mov_b32_e32 v49, 0
	v_mov_b32_e32 v50, 0
	v_mov_b32_e32 v51, 0
	v_mov_b32_e32 v52, 0
	v_mov_b32_e32 v53, 0
	v_mov_b32_e32 v54, 0
	v_mov_b32_e32 v55, 0
	v_mov_b32_e32 v56, 0
	v_mov_b32_e32 v57, 0
	v_mov_b32_e32 v58, 0
	v_mov_b32_e32 v59, 0
	v_mov_b32_e32 v60, 0
	v_mov_b32_e32 v61, 0
	v_mov_b32_e32 v62, 0
	v_mov_b32_e32 v63, 0
	v_add_u32_e32 v214, 0xffffff00, v212
	s_branch .Lhc0_blk

; __device__ __forceinline__ unsigned pk2(float lo, float hi) { unsigned r; asm("v_cvt_pk_bf16_f32 %0, %1, %2" : "=v"(r) : "v"(lo), "v"(hi)); return r; }
; __device__ __forceinline__ float bf2f(bf16_t b) { return __uint_as_float(((unsigned)b) << 16); }
; template <int EPI>
; __device__ __forceinline__ void hy_conv(const Args& a, int L, int c, const bf16_t* U, LAS unsigned char* lds) {
;     ...
; #pragma unroll
;         for (int tt = 0; tt < 4; ++tt)
; #pragma unroll
;             for (int i = 0; i < 16; ++i) {
;                 const int bb = (i & 3) + 8 * (i >> 2) + 4 * h, t = 32 * (tb + tt) + n;
;                 const size_t tok = (size_t)bb * SEQ + t;
;                 if (EPI == 0) {
;                     const float v = bf2f(UC[(size_t)c * MTOK + tok]), x1 = bf2f(UC[((size_t)256 + c) * MTOK + tok]);
;                     const float z = x1 * (acc[tt][i] + dbias * v);
;                     Z[tok] = (bf16_t)(pk2(z, 0.f) & 0xffffu);
;                 } else {
;                     const float zz = bf2f(Z[tok]), x2 = bf2f(UC[((size_t)512 + c) * MTOK + tok]);
;                     const float o = x2 * (acc[tt][i] + dbias * zz);
;                     MIX[tok * DM + 384 + c] = (bf16_t)(pk2(o, 0.f) & 0xffffu);
;                 }
.Lhc1_last:
	v_mfma_f32_32x32x16_bf16 v[48:63], v[80:83], v[196:199], v[48:63]
	v_mfma_f32_32x32x16_bf16 v[32:47], v[80:83], v[188:191], v[32:47]
	v_mfma_f32_32x32x16_bf16 v[16:31], v[80:83], v[144:147], v[16:31]
	v_mfma_f32_32x32x16_bf16 v[0:15], v[80:83], v[136:139], v[0:15]
	v_mfma_f32_32x32x16_bf16 v[48:63], v[84:87], v[200:203], v[48:63]
	v_mfma_f32_32x32x16_bf16 v[32:47], v[84:87], v[192:195], v[32:47]
	v_mfma_f32_32x32x16_bf16 v[16:31], v[84:87], v[148:151], v[16:31]
	v_mfma_f32_32x32x16_bf16 v[0:15], v[84:87], v[140:143], v[0:15]
	v_mfma_f32_32x32x16_bf16 v[48:63], v[88:91], v[204:207], v[48:63]
	v_mfma_f32_32x32x16_bf16 v[32:47], v[88:91], v[196:199], v[32:47]
	v_mfma_f32_32x32x16_bf16 v[16:31], v[88:91], v[188:191], v[16:31]
	v_mfma_f32_32x32x16_bf16 v[0:15], v[88:91], v[144:147], v[0:15]
	v_mfma_f32_32x32x16_bf16 v[48:63], v[92:95], v[216:219], v[48:63]
	v_mfma_f32_32x32x16_bf16 v[32:47], v[92:95], v[200:203], v[32:47]
	v_mfma_f32_32x32x16_bf16 v[16:31], v[92:95], v[192:195], v[16:31]
	v_mfma_f32_32x32x16_bf16 v[0:15], v[92:95], v[148:151], v[0:15]
	v_mov_b32_e32 v213, v215
	s_add_u32 s26, s26, 1
	s_lshr_b32 s30, s26, 3
	s_sub_u32 s30, s30, 1
	s_lshl_b32 s30, s30, 2
	v_and_b32_e32 v138, 63, v225
	v_lshrrev_b32_e32 v142, 6, v225
	v_lshrrev_b32_e32 v140, 2, v138
	v_and_b32_e32 v141, 3, v138
	v_lshlrev_b32_e32 v143, 4, v141
	v_lshl_or_b32 v143, v140, 12, v143
	v_lshl_or_b32 v143, v142, 9, v143
	s_lshl_b32 s28, s30, 6
	v_or_b32_e32 v143, s28, v143
	v_add_u32_e32 v144, 0x10000, v143
	v_and_b32_e32 v139, 31, v138
	v_lshrrev_b32_e32 v137, 5, v138
	v_lshlrev_b32_e32 v145, 2, v139
	v_lshl_or_b32 v145, v137, 9, v145
	v_lshl_or_b32 v145, v142, 11, v145
	v_add_u32_e32 v146, 0x24000, v145
	v_add_u32_e32 v145, 0x10200, v145
	v_lshlrev_b32_e32 v147, 5, v141
	v_lshl_or_b32 v147, v140, 7, v147
	v_lshl_or_b32 v147, v142, 11, v147
	v_add_u32_e32 v148, 0x24000, v147
	v_add_u32_e32 v147, 0x10200, v147
	global_load_dwordx4 v[64:67], v143, s[0:1] offset:0
	global_load_dwordx4 v[68:71], v143, s[2:3] offset:0
	global_load_dwordx4 v[72:75], v144, s[0:1] offset:0
	global_load_dwordx4 v[76:79], v144, s[2:3] offset:0
	global_load_dwordx4 v[80:83], v143, s[0:1] offset:64
	global_load_dwordx4 v[84:87], v143, s[2:3] offset:64
	global_load_dwordx4 v[88:91], v144, s[0:1] offset:64
	global_load_dwordx4 v[92:95], v144, s[2:3] offset:64
	global_load_dwordx4 v[96:99], v143, s[0:1] offset:128
	global_load_dwordx4 v[100:103], v143, s[2:3] offset:128
	global_load_dwordx4 v[104:107], v144, s[0:1] offset:128
	global_load_dwordx4 v[108:111], v144, s[2:3] offset:128
	global_load_dwordx4 v[112:115], v143, s[0:1] offset:192
	global_load_dwordx4 v[116:119], v143, s[2:3] offset:192
	global_load_dwordx4 v[120:123], v144, s[0:1] offset:192
	global_load_dwordx4 v[124:127], v144, s[2:3] offset:192
	ds_write_b32 v145, v48 offset:0
	ds_write_b32 v145, v49 offset:128
	ds_write_b32 v145, v50 offset:256
	ds_write_b32 v145, v51 offset:384
	ds_write_b32 v145, v52 offset:1024
	ds_write_b32 v145, v53 offset:1152
	ds_write_b32 v145, v54 offset:1280
	ds_write_b32 v145, v55 offset:1408
	s_waitcnt lgkmcnt(0)
	ds_read_b128 v[128:131], v147
	ds_read_b128 v[132:135], v147 offset:16
	ds_write_b32 v146, v56 offset:0
	ds_write_b32 v146, v57 offset:128
	ds_write_b32 v146, v58 offset:256
	ds_write_b32 v146, v59 offset:384
	ds_write_b32 v146, v60 offset:1024
	ds_write_b32 v146, v61 offset:1152
	ds_write_b32 v146, v62 offset:1280
	ds_write_b32 v146, v63 offset:1408
	s_waitcnt lgkmcnt(8)
	s_waitcnt vmcnt(14)
	v_lshlrev_b32_e32 v136, 16, v64
	v_lshlrev_b32_e32 v137, 16, v68
	v_fmac_f32_e32 v128, v178, v136
	v_mul_f32_e32 v128, v128, v137
	v_and_b32_e32 v136, 0xffff0000, v64
	v_and_b32_e32 v137, 0xffff0000, v68
	v_fmac_f32_e32 v129, v178, v136
	v_mul_f32_e32 v129, v129, v137
	v_lshlrev_b32_e32 v136, 16, v65
	v_lshlrev_b32_e32 v137, 16, v69
	v_fmac_f32_e32 v130, v178, v136
	v_mul_f32_e32 v130, v130, v137
	v_and_b32_e32 v136, 0xffff0000, v65
	v_and_b32_e32 v137, 0xffff0000, v69
	v_fmac_f32_e32 v131, v178, v136
	v_mul_f32_e32 v131, v131, v137
	v_lshlrev_b32_e32 v136, 16, v66
	v_lshlrev_b32_e32 v137, 16, v70
	v_fmac_f32_e32 v132, v178, v136
	v_mul_f32_e32 v132, v132, v137
	v_and_b32_e32 v136, 0xffff0000, v66
	v_and_b32_e32 v137, 0xffff0000, v70
	v_fmac_f32_e32 v133, v178, v136
	v_mul_f32_e32 v133, v133, v137
	v_lshlrev_b32_e32 v136, 16, v67
	v_lshlrev_b32_e32 v137, 16, v71
	v_fmac_f32_e32 v134, v178, v136
	v_mul_f32_e32 v134, v134, v137
	v_and_b32_e32 v136, 0xffff0000, v67
	v_and_b32_e32 v137, 0xffff0000, v71
	v_fmac_f32_e32 v135, v178, v136
	v_mul_f32_e32 v135, v135, v137
	v_cvt_pk_bf16_f32 v64, v128, v129
	v_cvt_pk_bf16_f32 v65, v130, v131
	v_cvt_pk_bf16_f32 v66, v132, v133
	v_cvt_pk_bf16_f32 v67, v134, v135
	global_store_dwordx4 v143, v[64:67], s[20:21] offset:0
	s_waitcnt lgkmcnt(0)
	ds_read_b128 v[128:131], v148
	ds_read_b128 v[132:135], v148 offset:16
	ds_write_b32 v145, v32 offset:0
	ds_write_b32 v145, v33 offset:128
	ds_write_b32 v145, v34 offset:256
	ds_write_b32 v145, v35 offset:384
	ds_write_b32 v145, v36 offset:1024
	ds_write_b32 v145, v37 offset:1152
	ds_write_b32 v145, v38 offset:1280
	ds_write_b32 v145, v39 offset:1408
	s_waitcnt lgkmcnt(8)
	s_waitcnt vmcnt(13)
; __device__ __forceinline__ unsigned pk2(float lo, float hi) { unsigned r; asm("v_cvt_pk_bf16_f32 %0, %1, %2" : "=v"(r) : "v"(lo), "v"(hi)); return r; }
; __device__ __forceinline__ float bf2f(bf16_t b) { return __uint_as_float(((unsigned)b) << 16); }
; template <int EPI>
; __device__ __forceinline__ void hy_conv(const Args& a, int L, int c, const bf16_t* U, LAS unsigned char* lds) {
;     ...
;         for (int tt = 0; tt < 4; ++tt)
; #pragma unroll
;             for (int i = 0; i < 16; ++i) {
;                 const int bb = (i & 3) + 8 * (i >> 2) + 4 * h, t = 32 * (tb + tt) + n;
;                 const size_t tok = (size_t)bb * SEQ + t;
;                 if (EPI == 0) {
;                     const float v = bf2f(UC[(size_t)c * MTOK + tok]), x1 = bf2f(UC[((size_t)256 + c) * MTOK + tok]);
;                     const float z = x1 * (acc[tt][i] + dbias * v);
;                     Z[tok] = (bf16_t)(pk2(z, 0.f) & 0xffffu);
;                 } else {
;                     const float zz = bf2f(Z[tok]), x2 = bf2f(UC[((size_t)512 + c) * MTOK + tok]);
;                     const float o = x2 * (acc[tt][i] + dbias * zz);
;                     MIX[tok * DM + 384 + c] = (bf16_t)(pk2(o, 0.f) & 0xffffu);
;                 }
	v_lshlrev_b32_e32 v136, 16, v72
	v_lshlrev_b32_e32 v137, 16, v76
	v_fmac_f32_e32 v128, v178, v136
	v_mul_f32_e32 v128, v128, v137
	v_and_b32_e32 v136, 0xffff0000, v72
	v_and_b32_e32 v137, 0xffff0000, v76
	v_fmac_f32_e32 v129, v178, v136
	v_mul_f32_e32 v129, v129, v137
	v_lshlrev_b32_e32 v136, 16, v73
	v_lshlrev_b32_e32 v137, 16, v77
	v_fmac_f32_e32 v130, v178, v136
	v_mul_f32_e32 v130, v130, v137
	v_and_b32_e32 v136, 0xffff0000, v73
	v_and_b32_e32 v137, 0xffff0000, v77
	v_fmac_f32_e32 v131, v178, v136
	v_mul_f32_e32 v131, v131, v137
	v_lshlrev_b32_e32 v136, 16, v74
	v_lshlrev_b32_e32 v137, 16, v78
	v_fmac_f32_e32 v132, v178, v136
	v_mul_f32_e32 v132, v132, v137
	v_and_b32_e32 v136, 0xffff0000, v74
	v_and_b32_e32 v137, 0xffff0000, v78
	v_fmac_f32_e32 v133, v178, v136
	v_mul_f32_e32 v133, v133, v137
	v_lshlrev_b32_e32 v136, 16, v75
	v_lshlrev_b32_e32 v137, 16, v79
	v_fmac_f32_e32 v134, v178, v136
	v_mul_f32_e32 v134, v134, v137
	v_and_b32_e32 v136, 0xffff0000, v75
	v_and_b32_e32 v137, 0xffff0000, v79
	v_fmac_f32_e32 v135, v178, v136
	v_mul_f32_e32 v135, v135, v137
	v_cvt_pk_bf16_f32 v72, v128, v129
	v_cvt_pk_bf16_f32 v73, v130, v131
	v_cvt_pk_bf16_f32 v74, v132, v133
	v_cvt_pk_bf16_f32 v75, v134, v135
	global_store_dwordx4 v144, v[72:75], s[20:21] offset:0
	s_waitcnt lgkmcnt(0)
	ds_read_b128 v[128:131], v147
	ds_read_b128 v[132:135], v147 offset:16
	ds_write_b32 v146, v40 offset:0
	ds_write_b32 v146, v41 offset:128
	ds_write_b32 v146, v42 offset:256
	ds_write_b32 v146, v43 offset:384
	ds_write_b32 v146, v44 offset:1024
	ds_write_b32 v146, v45 offset:1152
	ds_write_b32 v146, v46 offset:1280
	ds_write_b32 v146, v47 offset:1408
	s_waitcnt lgkmcnt(8)
	s_waitcnt vmcnt(12)
	v_lshlrev_b32_e32 v136, 16, v80
	v_lshlrev_b32_e32 v137, 16, v84
	v_fmac_f32_e32 v128, v178, v136
	v_mul_f32_e32 v128, v128, v137
	v_and_b32_e32 v136, 0xffff0000, v80
	v_and_b32_e32 v137, 0xffff0000, v84
	v_fmac_f32_e32 v129, v178, v136
	v_mul_f32_e32 v129, v129, v137
	v_lshlrev_b32_e32 v136, 16, v81
	v_lshlrev_b32_e32 v137, 16, v85
	v_fmac_f32_e32 v130, v178, v136
	v_mul_f32_e32 v130, v130, v137
	v_and_b32_e32 v136, 0xffff0000, v81
	v_and_b32_e32 v137, 0xffff0000, v85
	v_fmac_f32_e32 v131, v178, v136
	v_mul_f32_e32 v131, v131, v137
	v_lshlrev_b32_e32 v136, 16, v82
	v_lshlrev_b32_e32 v137, 16, v86
	v_fmac_f32_e32 v132, v178, v136
	v_mul_f32_e32 v132, v132, v137
	v_and_b32_e32 v136, 0xffff0000, v82
	v_and_b32_e32 v137, 0xffff0000, v86
	v_fmac_f32_e32 v133, v178, v136
	v_mul_f32_e32 v133, v133, v137
	v_lshlrev_b32_e32 v136, 16, v83
	v_lshlrev_b32_e32 v137, 16, v87
	v_fmac_f32_e32 v134, v178, v136
	v_mul_f32_e32 v134, v134, v137
	v_and_b32_e32 v136, 0xffff0000, v83
	v_and_b32_e32 v137, 0xffff0000, v87
	v_fmac_f32_e32 v135, v178, v136
	v_mul_f32_e32 v135, v135, v137
	v_cvt_pk_bf16_f32 v80, v128, v129
	v_cvt_pk_bf16_f32 v81, v130, v131
	v_cvt_pk_bf16_f32 v82, v132, v133
	v_cvt_pk_bf16_f32 v83, v134, v135
	global_store_dwordx4 v143, v[80:83], s[20:21] offset:64
	s_waitcnt lgkmcnt(0)
	ds_read_b128 v[128:131], v148
	ds_read_b128 v[132:135], v148 offset:16
	ds_write_b32 v145, v16 offset:0
	ds_write_b32 v145, v17 offset:128
	ds_write_b32 v145, v18 offset:256
	ds_write_b32 v145, v19 offset:384
	ds_write_b32 v145, v20 offset:1024
	ds_write_b32 v145, v21 offset:1152
	ds_write_b32 v145, v22 offset:1280
	ds_write_b32 v145, v23 offset:1408
	s_waitcnt lgkmcnt(8)
	s_waitcnt vmcnt(11)
	v_lshlrev_b32_e32 v136, 16, v88
	v_lshlrev_b32_e32 v137, 16, v92
	v_fmac_f32_e32 v128, v178, v136
	v_mul_f32_e32 v128, v128, v137
	v_and_b32_e32 v136, 0xffff0000, v88
	v_and_b32_e32 v137, 0xffff0000, v92
	v_fmac_f32_e32 v129, v178, v136
	v_mul_f32_e32 v129, v129, v137
	v_lshlrev_b32_e32 v136, 16, v89
	v_lshlrev_b32_e32 v137, 16, v93
	v_fmac_f32_e32 v130, v178, v136
	v_mul_f32_e32 v130, v130, v137
	v_and_b32_e32 v136, 0xffff0000, v89
	v_and_b32_e32 v137, 0xffff0000, v93
	v_fmac_f32_e32 v131, v178, v136
	v_mul_f32_e32 v131, v131, v137
	v_lshlrev_b32_e32 v136, 16, v90
	v_lshlrev_b32_e32 v137, 16, v94
	v_fmac_f32_e32 v132, v178, v136
	v_mul_f32_e32 v132, v132, v137
	v_and_b32_e32 v136, 0xffff0000, v90
	v_and_b32_e32 v137, 0xffff0000, v94
	v_fmac_f32_e32 v133, v178, v136
	v_mul_f32_e32 v133, v133, v137
	v_lshlrev_b32_e32 v136, 16, v91
	v_lshlrev_b32_e32 v137, 16, v95
	v_fmac_f32_e32 v134, v178, v136
	v_mul_f32_e32 v134, v134, v137
	v_and_b32_e32 v136, 0xffff0000, v91
	v_and_b32_e32 v137, 0xffff0000, v95
	v_fmac_f32_e32 v135, v178, v136
	v_mul_f32_e32 v135, v135, v137
	v_cvt_pk_bf16_f32 v88, v128, v129
	v_cvt_pk_bf16_f32 v89, v130, v131
	v_cvt_pk_bf16_f32 v90, v132, v133
	v_cvt_pk_bf16_f32 v91, v134, v135
	global_store_dwordx4 v144, v[88:91], s[20:21] offset:64
	s_waitcnt lgkmcnt(0)
	ds_read_b128 v[128:131], v147
	ds_read_b128 v[132:135], v147 offset:16
	ds_write_b32 v146, v24 offset:0
	ds_write_b32 v146, v25 offset:128
	ds_write_b32 v146, v26 offset:256
	ds_write_b32 v146, v27 offset:384
	ds_write_b32 v146, v28 offset:1024
	ds_write_b32 v146, v29 offset:1152
	ds_write_b32 v146, v30 offset:1280
	ds_write_b32 v146, v31 offset:1408
	s_waitcnt lgkmcnt(8)
	s_waitcnt vmcnt(10)
; __device__ __forceinline__ unsigned pk2(float lo, float hi) { unsigned r; asm("v_cvt_pk_bf16_f32 %0, %1, %2" : "=v"(r) : "v"(lo), "v"(hi)); return r; }
; __device__ __forceinline__ float bf2f(bf16_t b) { return __uint_as_float(((unsigned)b) << 16); }
; template <int EPI>
; __device__ __forceinline__ void hy_conv(const Args& a, int L, int c, const bf16_t* U, LAS unsigned char* lds) {
;     ...
;         for (int tt = 0; tt < 4; ++tt)
; #pragma unroll
;             for (int i = 0; i < 16; ++i) {
;                 const int bb = (i & 3) + 8 * (i >> 2) + 4 * h, t = 32 * (tb + tt) + n;
;                 const size_t tok = (size_t)bb * SEQ + t;
;                 if (EPI == 0) {
;                     const float v = bf2f(UC[(size_t)c * MTOK + tok]), x1 = bf2f(UC[((size_t)256 + c) * MTOK + tok]);
;                     const float z = x1 * (acc[tt][i] + dbias * v);
;                     Z[tok] = (bf16_t)(pk2(z, 0.f) & 0xffffu);
;                 } else {
;                     const float zz = bf2f(Z[tok]), x2 = bf2f(UC[((size_t)512 + c) * MTOK + tok]);
;                     const float o = x2 * (acc[tt][i] + dbias * zz);
;                     MIX[tok * DM + 384 + c] = (bf16_t)(pk2(o, 0.f) & 0xffffu);
;                 }
	v_lshlrev_b32_e32 v136, 16, v96
	v_lshlrev_b32_e32 v137, 16, v100
	v_fmac_f32_e32 v128, v178, v136
	v_mul_f32_e32 v128, v128, v137
	v_and_b32_e32 v136, 0xffff0000, v96
	v_and_b32_e32 v137, 0xffff0000, v100
	v_fmac_f32_e32 v129, v178, v136
	v_mul_f32_e32 v129, v129, v137
	v_lshlrev_b32_e32 v136, 16, v97
	v_lshlrev_b32_e32 v137, 16, v101
	v_fmac_f32_e32 v130, v178, v136
	v_mul_f32_e32 v130, v130, v137
	v_and_b32_e32 v136, 0xffff0000, v97
	v_and_b32_e32 v137, 0xffff0000, v101
	v_fmac_f32_e32 v131, v178, v136
	v_mul_f32_e32 v131, v131, v137
	v_lshlrev_b32_e32 v136, 16, v98
	v_lshlrev_b32_e32 v137, 16, v102
	v_fmac_f32_e32 v132, v178, v136
	v_mul_f32_e32 v132, v132, v137
	v_and_b32_e32 v136, 0xffff0000, v98
	v_and_b32_e32 v137, 0xffff0000, v102
	v_fmac_f32_e32 v133, v178, v136
	v_mul_f32_e32 v133, v133, v137
	v_lshlrev_b32_e32 v136, 16, v99
	v_lshlrev_b32_e32 v137, 16, v103
	v_fmac_f32_e32 v134, v178, v136
	v_mul_f32_e32 v134, v134, v137
	v_and_b32_e32 v136, 0xffff0000, v99
	v_and_b32_e32 v137, 0xffff0000, v103
	v_fmac_f32_e32 v135, v178, v136
	v_mul_f32_e32 v135, v135, v137
	v_cvt_pk_bf16_f32 v96, v128, v129
	v_cvt_pk_bf16_f32 v97, v130, v131
	v_cvt_pk_bf16_f32 v98, v132, v133
	v_cvt_pk_bf16_f32 v99, v134, v135
	global_store_dwordx4 v143, v[96:99], s[20:21] offset:128
	s_waitcnt lgkmcnt(0)
	ds_read_b128 v[128:131], v148
	ds_read_b128 v[132:135], v148 offset:16
	ds_write_b32 v145, v0 offset:0
	ds_write_b32 v145, v1 offset:128
	ds_write_b32 v145, v2 offset:256
	ds_write_b32 v145, v3 offset:384
	ds_write_b32 v145, v4 offset:1024
	ds_write_b32 v145, v5 offset:1152
	ds_write_b32 v145, v6 offset:1280
	ds_write_b32 v145, v7 offset:1408
	s_waitcnt lgkmcnt(8)
	s_waitcnt vmcnt(9)
	v_lshlrev_b32_e32 v136, 16, v104
	v_lshlrev_b32_e32 v137, 16, v108
	v_fmac_f32_e32 v128, v178, v136
	v_mul_f32_e32 v128, v128, v137
	v_and_b32_e32 v136, 0xffff0000, v104
	v_and_b32_e32 v137, 0xffff0000, v108
	v_fmac_f32_e32 v129, v178, v136
	v_mul_f32_e32 v129, v129, v137
	v_lshlrev_b32_e32 v136, 16, v105
	v_lshlrev_b32_e32 v137, 16, v109
	v_fmac_f32_e32 v130, v178, v136
	v_mul_f32_e32 v130, v130, v137
	v_and_b32_e32 v136, 0xffff0000, v105
	v_and_b32_e32 v137, 0xffff0000, v109
	v_fmac_f32_e32 v131, v178, v136
	v_mul_f32_e32 v131, v131, v137
	v_lshlrev_b32_e32 v136, 16, v106
	v_lshlrev_b32_e32 v137, 16, v110
	v_fmac_f32_e32 v132, v178, v136
	v_mul_f32_e32 v132, v132, v137
	v_and_b32_e32 v136, 0xffff0000, v106
	v_and_b32_e32 v137, 0xffff0000, v110
	v_fmac_f32_e32 v133, v178, v136
	v_mul_f32_e32 v133, v133, v137
	v_lshlrev_b32_e32 v136, 16, v107
	v_lshlrev_b32_e32 v137, 16, v111
	v_fmac_f32_e32 v134, v178, v136
	v_mul_f32_e32 v134, v134, v137
	v_and_b32_e32 v136, 0xffff0000, v107
	v_and_b32_e32 v137, 0xffff0000, v111
	v_fmac_f32_e32 v135, v178, v136
	v_mul_f32_e32 v135, v135, v137
	v_cvt_pk_bf16_f32 v104, v128, v129
	v_cvt_pk_bf16_f32 v105, v130, v131
	v_cvt_pk_bf16_f32 v106, v132, v133
	v_cvt_pk_bf16_f32 v107, v134, v135
	global_store_dwordx4 v144, v[104:107], s[20:21] offset:128
	s_waitcnt lgkmcnt(0)
	ds_read_b128 v[128:131], v147
	ds_read_b128 v[132:135], v147 offset:16
	ds_write_b32 v146, v8 offset:0
	ds_write_b32 v146, v9 offset:128
	ds_write_b32 v146, v10 offset:256
	ds_write_b32 v146, v11 offset:384
	ds_write_b32 v146, v12 offset:1024
	ds_write_b32 v146, v13 offset:1152
	ds_write_b32 v146, v14 offset:1280
	ds_write_b32 v146, v15 offset:1408
	s_waitcnt lgkmcnt(8)
	s_waitcnt vmcnt(8)
	v_lshlrev_b32_e32 v136, 16, v112
	v_lshlrev_b32_e32 v137, 16, v116
	v_fmac_f32_e32 v128, v178, v136
	v_mul_f32_e32 v128, v128, v137
	v_and_b32_e32 v136, 0xffff0000, v112
	v_and_b32_e32 v137, 0xffff0000, v116
	v_fmac_f32_e32 v129, v178, v136
	v_mul_f32_e32 v129, v129, v137
	v_lshlrev_b32_e32 v136, 16, v113
	v_lshlrev_b32_e32 v137, 16, v117
	v_fmac_f32_e32 v130, v178, v136
	v_mul_f32_e32 v130, v130, v137
	v_and_b32_e32 v136, 0xffff0000, v113
	v_and_b32_e32 v137, 0xffff0000, v117
	v_fmac_f32_e32 v131, v178, v136
	v_mul_f32_e32 v131, v131, v137
	v_lshlrev_b32_e32 v136, 16, v114
	v_lshlrev_b32_e32 v137, 16, v118
	v_fmac_f32_e32 v132, v178, v136
	v_mul_f32_e32 v132, v132, v137
	v_and_b32_e32 v136, 0xffff0000, v114
	v_and_b32_e32 v137, 0xffff0000, v118
	v_fmac_f32_e32 v133, v178, v136
	v_mul_f32_e32 v133, v133, v137
	v_lshlrev_b32_e32 v136, 16, v115
	v_lshlrev_b32_e32 v137, 16, v119
	v_fmac_f32_e32 v134, v178, v136
	v_mul_f32_e32 v134, v134, v137
	v_and_b32_e32 v136, 0xffff0000, v115
	v_and_b32_e32 v137, 0xffff0000, v119
	v_fmac_f32_e32 v135, v178, v136
	v_mul_f32_e32 v135, v135, v137
	v_cvt_pk_bf16_f32 v112, v128, v129
	v_cvt_pk_bf16_f32 v113, v130, v131
	v_cvt_pk_bf16_f32 v114, v132, v133
	v_cvt_pk_bf16_f32 v115, v134, v135
	global_store_dwordx4 v143, v[112:115], s[20:21] offset:192
	s_waitcnt lgkmcnt(0)
	ds_read_b128 v[128:131], v148
	ds_read_b128 v[132:135], v148 offset:16
	s_waitcnt lgkmcnt(0)
	s_waitcnt vmcnt(7)
	v_lshlrev_b32_e32 v136, 16, v120
	v_lshlrev_b32_e32 v137, 16, v124
	v_fmac_f32_e32 v128, v178, v136
	v_mul_f32_e32 v128, v128, v137
	v_and_b32_e32 v136, 0xffff0000, v120
	v_and_b32_e32 v137, 0xffff0000, v124
	v_fmac_f32_e32 v129, v178, v136
	v_mul_f32_e32 v129, v129, v137
	v_lshlrev_b32_e32 v136, 16, v121
	v_lshlrev_b32_e32 v137, 16, v125
	v_fmac_f32_e32 v130, v178, v136
	v_mul_f32_e32 v130, v130, v137
	v_and_b32_e32 v136, 0xffff0000, v121
	v_and_b32_e32 v137, 0xffff0000, v125
	v_fmac_f32_e32 v131, v178, v136
	v_mul_f32_e32 v131, v131, v137
	v_lshlrev_b32_e32 v136, 16, v122
	v_lshlrev_b32_e32 v137, 16, v126
	v_fmac_f32_e32 v132, v178, v136
	v_mul_f32_e32 v132, v132, v137
	v_and_b32_e32 v136, 0xffff0000, v122
	v_and_b32_e32 v137, 0xffff0000, v126
	v_fmac_f32_e32 v133, v178, v136
	v_mul_f32_e32 v133, v133, v137
	v_lshlrev_b32_e32 v136, 16, v123
	v_lshlrev_b32_e32 v137, 16, v127
	v_fmac_f32_e32 v134, v178, v136
	v_mul_f32_e32 v134, v134, v137
	v_and_b32_e32 v136, 0xffff0000, v123
	v_and_b32_e32 v137, 0xffff0000, v127
	v_fmac_f32_e32 v135, v178, v136
	v_mul_f32_e32 v135, v135, v137
	v_cvt_pk_bf16_f32 v120, v128, v129
	v_cvt_pk_bf16_f32 v121, v130, v131
	v_cvt_pk_bf16_f32 v122, v132, v133
	v_cvt_pk_bf16_f32 v123, v134, v135
	global_store_dwordx4 v144, v[120:123], s[20:21] offset:192
	s_cmp_eq_u32 s26, 16
	s_cbranch_scc1 .Lhc1_done
; template <int EPI>
; __device__ __forceinline__ void hy_conv(const Args& a, int L, int c, const bf16_t* U, LAS unsigned char* lds) {
;     ...
;     for (int blk = 0; blk < 2; ++blk) {
;         const int tb = 8 * wid + 4 * blk;
;         f32x16 acc[4];
; #pragma unroll
;         for (int tt = 0; tt < 4; ++tt)
; #pragma unroll
;             for (int i = 0; i < 16; ++i) acc[tt][i] = 0.f;
;         bf16x8 an[4];
; #pragma unroll
;         for (int k = 0; k < 4; ++k) an[k] = *(const bf16x8*)(urow + 16 * k);
; #pragma unroll 1
	v_mov_b32_e32 v0, 0
	v_mov_b32_e32 v1, 0
	v_mov_b32_e32 v2, 0
	v_mov_b32_e32 v3, 0
	v_mov_b32_e32 v4, 0
	v_mov_b32_e32 v5, 0
	v_mov_b32_e32 v6, 0
	v_mov_b32_e32 v7, 0
	v_mov_b32_e32 v8, 0
	v_mov_b32_e32 v9, 0
	v_mov_b32_e32 v10, 0
	v_mov_b32_e32 v11, 0
	v_mov_b32_e32 v12, 0
	v_mov_b32_e32 v13, 0
	v_mov_b32_e32 v14, 0
	v_mov_b32_e32 v15, 0
	v_mov_b32_e32 v16, 0
	v_mov_b32_e32 v17, 0
	v_mov_b32_e32 v18, 0
	v_mov_b32_e32 v19, 0
	v_mov_b32_e32 v20, 0
	v_mov_b32_e32 v21, 0
	v_mov_b32_e32 v22, 0
	v_mov_b32_e32 v23, 0
	v_mov_b32_e32 v24, 0
	v_mov_b32_e32 v25, 0
	v_mov_b32_e32 v26, 0
	v_mov_b32_e32 v27, 0
	v_mov_b32_e32 v28, 0
	v_mov_b32_e32 v29, 0
	v_mov_b32_e32 v30, 0
	v_mov_b32_e32 v31, 0
	v_mov_b32_e32 v32, 0
	v_mov_b32_e32 v33, 0
	v_mov_b32_e32 v34, 0
	v_mov_b32_e32 v35, 0
	v_mov_b32_e32 v36, 0
	v_mov_b32_e32 v37, 0
	v_mov_b32_e32 v38, 0
	v_mov_b32_e32 v39, 0
	v_mov_b32_e32 v40, 0
	v_mov_b32_e32 v41, 0
	v_mov_b32_e32 v42, 0
	v_mov_b32_e32 v43, 0
	v_mov_b32_e32 v44, 0
	v_mov_b32_e32 v45, 0
	v_mov_b32_e32 v46, 0
	v_mov_b32_e32 v47, 0
	v_mov_b32_e32 v48, 0
	v_mov_b32_e32 v49, 0
	v_mov_b32_e32 v50, 0
	v_mov_b32_e32 v51, 0
	v_mov_b32_e32 v52, 0
	v_mov_b32_e32 v53, 0
	v_mov_b32_e32 v54, 0
	v_mov_b32_e32 v55, 0
	v_mov_b32_e32 v56, 0
	v_mov_b32_e32 v57, 0
	v_mov_b32_e32 v58, 0
	v_mov_b32_e32 v59, 0
	v_mov_b32_e32 v60, 0
	v_mov_b32_e32 v61, 0
	v_mov_b32_e32 v62, 0
	v_mov_b32_e32 v63, 0
	v_add_u32_e32 v214, 0xffffff00, v212
	s_branch .Lhc1_blk

; __device__ __forceinline__ void run_phase(const Args& a0, int ph, LAS unsigned char* lds) {
;     ...
;         if (G == 256) {
;             for (int k = 0; k < 3; ++k) attnC_unit(a, 96 * (c & 7) + 32 * k + (c >> 3), lds);
;             __syncthreads();
;             for (int k = 0; k < 3; ++k) { attnA_unit(a, 96 * (c & 7) + 32 * k + (c >> 3), lds); __syncthreads(); }
.LBB0_250:
	s_and_b64 vcc, exec, s[0:1]
	s_cbranch_vccz .LBB0_284
	v_readfirstlane_b32 s2, v225
	s_cmp_ge_u32 s2, 0x100
	s_cbranch_scc0 .Lprio_skip
	s_setprio 1
.Lprio_skip:
	v_readlane_b32 s0, v255, 6
	v_readlane_b32 s1, v255, 7
	s_mov_b32 s2, s0
	s_and_b32 s0, s0, 7
	s_mulk_i32 s0, 0x60
	s_ashr_i32 s1, s2, 3
	s_add_i32 s17, s0, s1
	v_readlane_b32 s24, v254, 55
	v_readlane_b32 s25, v254, 56
	s_add_u32 s26, s24, 0xbf8a000
	s_addc_u32 s27, s25, 0
	s_add_u32 s6, s24, 0xc02b300
	v_mov_b32_e32 v240, 0x3e38aa3b
	v_mov_b32_e32 v238, 0x1600
	v_mov_b32_e32 v233, 1
	s_addc_u32 s7, s25, 0
	s_mov_b32 s8, 0
	s_movk_i32 s13, 0x1000
	s_mov_b32 s15, 0x51000
	s_mov_b32 s16, 0x21f8a000
	s_mov_b64 s[18:19], 0x50000
	s_mov_b64 s[20:21], 0x28000
	s_mov_b64 s[22:23], 0x21f8a500
	s_branch .LBB0_253

; __device__ __forceinline__ unsigned pk2n(float lo, float hi) { const f32x2v v = {lo, hi}; const bf16v2 b = __builtin_convertvector(v, bf16v2); return __builtin_bit_cast(unsigned, b); }
; __device__ __forceinline__ float fexp2(float x) { return __builtin_amdgcn_exp2f(x); }
; template <bool KLDS>
; __device__ __forceinline__ void attn_step(const bf16x8 (&kf)[4], LAS const unsigned char* kb, const bf16x8 (&vf)[2][2], const bf16x8 (&qf)[4], f32x16& o0, f32x16& o1, float& m, float& l, int lane, int maskmode) {
;     ...
;     const float mn = fmaxf(m, tm), al = fexp2(m - mn); m = mn;
;     float ps = 0.f;
; #pragma unroll
;     for (int i = 0; i < 16; ++i) { S[i] = fexp2(S[i] - mn); ps += S[i]; }
;     l = l * al + ps;
; #pragma unroll
;     for (int i = 0; i < 16; ++i) { o0[i] *= al; o1[i] *= al; }
;     bf16x8 pf[2];
; #pragma unroll
;     for (int s2 = 0; s2 < 2; ++s2) {
;         u32x4 w; w.x = pk2n(S[8 * s2 + 0], S[8 * s2 + 1]); w.y = pk2n(S[8 * s2 + 2], S[8 * s2 + 3]); w.z = pk2n(S[8 * s2 + 4], S[8 * s2 + 5]); w.w = pk2n(S[8 * s2 + 6], S[8 * s2 + 7]);
;         pf[s2] = __builtin_bit_cast(bf16x8, w);
;     }
; #pragma unroll
;     for (int s2 = 0; s2 < 2; ++s2) {
;         o0 = __builtin_amdgcn_mfma_f32_32x32x16_bf16(vf[s2][0], pf[s2], o0, 0, 0, 0);
;         o1 = __builtin_amdgcn_mfma_f32_32x32x16_bf16(vf[s2][1], pf[s2], o1, 0, 0, 0);
;     }
.LaP_nrzb:
	v_sub_f32_e32 v32, v32, v220
	v_sub_f32_e32 v96, v96, v222
	v_sub_f32_e32 v33, v33, v220
	v_sub_f32_e32 v97, v97, v222
	v_sub_f32_e32 v34, v34, v220
	v_sub_f32_e32 v98, v98, v222
	v_sub_f32_e32 v35, v35, v220
	v_sub_f32_e32 v99, v99, v222
	v_sub_f32_e32 v36, v36, v220
	v_sub_f32_e32 v100, v100, v222
	v_sub_f32_e32 v37, v37, v220
	v_sub_f32_e32 v101, v101, v222
	v_sub_f32_e32 v38, v38, v220
	v_sub_f32_e32 v102, v102, v222
	v_sub_f32_e32 v39, v39, v220
	v_sub_f32_e32 v103, v103, v222
	v_sub_f32_e32 v40, v40, v220
	v_sub_f32_e32 v104, v104, v222
	v_sub_f32_e32 v41, v41, v220
	v_sub_f32_e32 v105, v105, v222
	v_sub_f32_e32 v42, v42, v220
	v_sub_f32_e32 v106, v106, v222
	v_sub_f32_e32 v43, v43, v220
	v_sub_f32_e32 v107, v107, v222
	v_sub_f32_e32 v44, v44, v220
	v_sub_f32_e32 v108, v108, v222
	v_sub_f32_e32 v45, v45, v220
	v_sub_f32_e32 v109, v109, v222
	v_sub_f32_e32 v46, v46, v220
	v_sub_f32_e32 v110, v110, v222
	v_sub_f32_e32 v47, v47, v220
	v_sub_f32_e32 v111, v111, v222
	v_exp_f32_e32 v32, v32
	v_exp_f32_e32 v96, v96
	v_exp_f32_e32 v33, v33
	v_exp_f32_e32 v97, v97
	v_exp_f32_e32 v34, v34
	v_exp_f32_e32 v98, v98
	v_add_f32_e32 v152, v32, v33
	v_add_f32_e32 v218, v96, v97
	v_exp_f32_e32 v35, v35
	v_exp_f32_e32 v99, v99
	v_add_f32_e32 v153, v34, v35
	v_add_f32_e32 v219, v98, v99
	v_exp_f32_e32 v36, v36
	v_exp_f32_e32 v100, v100
	v_exp_f32_e32 v37, v37
	v_exp_f32_e32 v101, v101
	v_add_f32_e32 v153, v153, v36
	v_add_f32_e32 v219, v219, v100
	v_exp_f32_e32 v38, v38
	v_exp_f32_e32 v102, v102
	v_add_f32_e32 v152, v152, v37
	v_add_f32_e32 v218, v218, v101
	v_exp_f32_e32 v39, v39
	v_exp_f32_e32 v103, v103
	v_add_f32_e32 v153, v153, v38
	v_add_f32_e32 v219, v219, v102
	v_exp_f32_e32 v40, v40
	v_exp_f32_e32 v104, v104
	v_add_f32_e32 v152, v152, v39
	v_add_f32_e32 v218, v218, v103
	v_exp_f32_e32 v41, v41
	v_exp_f32_e32 v105, v105
	v_add_f32_e32 v153, v153, v40
	v_add_f32_e32 v219, v219, v104
	v_exp_f32_e32 v42, v42
	v_exp_f32_e32 v106, v106
	v_add_f32_e32 v152, v152, v41
	v_add_f32_e32 v218, v218, v105
	v_exp_f32_e32 v43, v43
	v_exp_f32_e32 v107, v107
	v_add_f32_e32 v153, v153, v42
	v_add_f32_e32 v219, v219, v106
	v_exp_f32_e32 v44, v44
	v_exp_f32_e32 v108, v108
	v_add_f32_e32 v152, v152, v43
	v_add_f32_e32 v218, v218, v107
	v_exp_f32_e32 v45, v45
	v_exp_f32_e32 v109, v109
	v_add_f32_e32 v153, v153, v44
	v_add_f32_e32 v219, v219, v108
	v_exp_f32_e32 v46, v46
	v_exp_f32_e32 v110, v110
	v_add_f32_e32 v152, v152, v45
	v_add_f32_e32 v218, v218, v109
	v_exp_f32_e32 v47, v47
	v_exp_f32_e32 v111, v111
	v_add_f32_e32 v153, v153, v46
	v_add_f32_e32 v219, v219, v110
	s_nop 0
	s_nop 0
	v_add_f32_e32 v153, v153, v47
	v_add_f32_e32 v219, v219, v111
	s_nop 0
	s_nop 0
	v_add_f32_e32 v152, v152, v153
	v_add_f32_e32 v218, v218, v219
	v_fma_f32 v135, v135, v140, v152
	v_fma_f32 v213, v213, v150, v218
	v_cvt_pk_bf16_f32 v32, v32, v33
	v_cvt_pk_bf16_f32 v96, v96, v97
	v_cvt_pk_bf16_f32 v33, v34, v35
	v_cvt_pk_bf16_f32 v97, v98, v99
	v_cvt_pk_bf16_f32 v34, v36, v37
	v_cvt_pk_bf16_f32 v98, v100, v101
	v_cvt_pk_bf16_f32 v35, v38, v39
	v_cvt_pk_bf16_f32 v99, v102, v103
	v_cvt_pk_bf16_f32 v36, v40, v41
	v_cvt_pk_bf16_f32 v100, v104, v105
	v_cvt_pk_bf16_f32 v37, v42, v43
	v_cvt_pk_bf16_f32 v101, v106, v107
	v_cvt_pk_bf16_f32 v38, v44, v45
	v_cvt_pk_bf16_f32 v102, v108, v109
	v_cvt_pk_bf16_f32 v39, v46, v47
	v_cvt_pk_bf16_f32 v103, v110, v111
	s_nop 0
	v_mfma_f32_32x32x16_bf16 v[16:31], v[160:163], v[32:35], v[16:31]
	v_mfma_f32_32x32x16_bf16 v[80:95], v[176:179], v[96:99], v[80:95]
	v_mfma_f32_32x32x16_bf16 v[0:15], v[164:167], v[32:35], v[0:15]
	v_mfma_f32_32x32x16_bf16 v[64:79], v[180:183], v[96:99], v[64:79]
	v_mfma_f32_32x32x16_bf16 v[16:31], v[168:171], v[36:39], v[16:31]
	v_mfma_f32_32x32x16_bf16 v[80:95], v[184:187], v[100:103], v[80:95]
	v_mfma_f32_32x32x16_bf16 v[0:15], v[172:175], v[36:39], v[0:15]
	v_mfma_f32_32x32x16_bf16 v[64:79], v[188:191], v[100:103], v[64:79]
	s_add_i32 s86, s86, 1
	s_add_i32 s2, s2, 1
	s_cmp_le_u32 s86, s87
	s_cbranch_scc1 .LaT_loop
; __device__ __forceinline__ unsigned pk2(float lo, float hi) { unsigned r; asm("v_cvt_pk_bf16_f32 %0, %1, %2" : "=v"(r) : "v"(lo), "v"(hi)); return r; }
; __device__ __forceinline__ void attnA_unit(const Args& a, int unit, LAS unsigned char* lds) {
;     ...
;             const float lt = l + __shfl_xor(l, 32);
;             const float inv = 1.0f / lt, lse = m + __builtin_amdgcn_logf(lt);
;             const size_t tokg = (size_t)b * SEQ + tq;
;             if (pidx < 2) {
;                 bf16_t* op = OA + ((size_t)pidx * MTOK + tokg) * 384 + 64 * hh;
; #pragma unroll
;                 for (int dt = 0; dt < 2; ++dt)
; #pragma unroll
;                     for (int g = 0; g < 4; ++g) {
;                         const f32x16& o = dt ? o1 : o0;
;                         u32x2 w; w.x = pk2(o[4 * g] * inv, o[4 * g + 1] * inv); w.y = pk2(o[4 * g + 2] * inv, o[4 * g + 3] * inv);
;                         *(u32x2*)(op + 32 * dt + 8 * g + 4 * h) = w;
;                     }
;                 if (h == 0) LSE[((size_t)pidx * MTOK + tokg) * 6 + hh] = lse;
	s_cmp_le_u32 s2, s3
	s_cbranch_scc1 .LaT_loop
	s_nop 15
	s_nop 7
	s_lshl_b32 s32, s83, 13
	v_mov_b32_e32 v39, v135
	s_nop 1
	v_permlane32_swap_b32_e32 v39, v135
	v_add_f32_e32 v63, v135, v39
	v_add_u32_e32 v40, s32, v192
	v_log_f32_e32 v34, v63
	v_div_scale_f32 v35, s[0:1], v63, v63, 1.0
	v_rcp_f32_e32 v37, v35
	v_div_scale_f32 v38, vcc, 1.0, v63, 1.0
	v_fma_f32 v62, -v35, v37, 1.0
	v_fmac_f32_e32 v37, v62, v37
	v_mul_f32_e32 v62, v38, v37
	v_fma_f32 v33, -v35, v62, v38
	v_fmac_f32_e32 v62, v33, v37
	v_fma_f32 v35, -v35, v62, v38
	v_div_fmas_f32 v35, v35, v37, v62
	v_div_fixup_f32 v33, v35, v63, 1.0
	v_add_f32_e32 v36, v137, v34
	s_lshl_b32 s80, 8, s73
	s_and_b64 vcc, exec, s[90:91]
	s_cbranch_vccz .LaT_mga
	v_mul_f32_e32 v52, v16, v33
	v_mul_f32_e32 v53, v17, v33
	v_mul_f32_e32 v54, v18, v33
	v_mul_f32_e32 v55, v19, v33
	v_cvt_pk_bf16_f32 v48, v52, v53
	v_cvt_pk_bf16_f32 v49, v54, v55
	v_xor_b32_e32 v41, 0x0, v40
	ds_write_b64 v41, v[48:49]
	v_mul_f32_e32 v52, v20, v33
	v_mul_f32_e32 v53, v21, v33
	v_mul_f32_e32 v54, v22, v33
	v_mul_f32_e32 v55, v23, v33
	v_cvt_pk_bf16_f32 v50, v52, v53
	v_cvt_pk_bf16_f32 v51, v54, v55
	v_xor_b32_e32 v41, 0x10, v40
	ds_write_b64 v41, v[50:51]
	v_mul_f32_e32 v52, v24, v33
	v_mul_f32_e32 v53, v25, v33
	v_mul_f32_e32 v54, v26, v33
	v_mul_f32_e32 v55, v27, v33
	v_cvt_pk_bf16_f32 v48, v52, v53
	v_cvt_pk_bf16_f32 v49, v54, v55
	v_xor_b32_e32 v41, 0x20, v40
	ds_write_b64 v41, v[48:49]
	v_mul_f32_e32 v52, v28, v33
	v_mul_f32_e32 v53, v29, v33
	v_mul_f32_e32 v54, v30, v33
	v_mul_f32_e32 v55, v31, v33
	v_cvt_pk_bf16_f32 v50, v52, v53
	v_cvt_pk_bf16_f32 v51, v54, v55
	v_xor_b32_e32 v41, 0x30, v40
	ds_write_b64 v41, v[50:51]
	v_mul_f32_e32 v52, v0, v33
	v_mul_f32_e32 v53, v1, v33
	v_mul_f32_e32 v54, v2, v33
	v_mul_f32_e32 v55, v3, v33
	v_cvt_pk_bf16_f32 v48, v52, v53
	v_cvt_pk_bf16_f32 v49, v54, v55
	v_xor_b32_e32 v41, 0x40, v40
	ds_write_b64 v41, v[48:49]
	v_mul_f32_e32 v52, v4, v33
	v_mul_f32_e32 v53, v5, v33
	v_mul_f32_e32 v54, v6, v33
	v_mul_f32_e32 v55, v7, v33
	v_cvt_pk_bf16_f32 v50, v52, v53
	v_cvt_pk_bf16_f32 v51, v54, v55
	v_xor_b32_e32 v41, 0x50, v40
	ds_write_b64 v41, v[50:51]
	v_mul_f32_e32 v52, v8, v33
	v_mul_f32_e32 v53, v9, v33
	v_mul_f32_e32 v54, v10, v33
	v_mul_f32_e32 v55, v11, v33
	v_cvt_pk_bf16_f32 v48, v52, v53
	v_cvt_pk_bf16_f32 v49, v54, v55
	v_xor_b32_e32 v41, 0x60, v40
	ds_write_b64 v41, v[48:49]
	v_mul_f32_e32 v52, v12, v33
	v_mul_f32_e32 v53, v13, v33
	v_mul_f32_e32 v54, v14, v33
	v_mul_f32_e32 v55, v15, v33
	v_cvt_pk_bf16_f32 v50, v52, v53
	v_cvt_pk_bf16_f32 v51, v54, v55
	v_xor_b32_e32 v41, 0x70, v40
	ds_write_b64 v41, v[50:51]
	v_readlane_b32 s0, v253, 6
	s_movk_i32 s1, 0x300
	v_add_u32_e32 v43, s0, v142
	v_add_u32_e32 v56, s0, v122
	v_mov_b32_e32 v44, s94
	v_mov_b32_e32 v45, s95
	v_add_co_u32_e32 v44, vcc, v44, v147
	s_nop 0
	v_addc_co_u32_e32 v45, vcc, 0, v45, vcc
	s_and_saveexec_b64 s[2:3], s[70:71]
	v_mad_u64_u32 v[58:59], s[98:99], v56, 24, s[88:89]
	global_store_dword v[58:59], v36, off
	s_or_b64 exec, exec, s[2:3]
	s_branch .LaT_fla

; __device__ __forceinline__ void run_phase(const Args& a0, int ph, LAS unsigned char* lds) {
;     ...
;             for (int k = 0; k < 3; ++k) { attnA_unit(a, 96 * (c & 7) + 32 * k + (c >> 3), lds); __syncthreads(); }
;         } else {
;             for (int u = c; u < 768; u += G) attnC_unit(a, u, lds);
;             __syncthreads();
;             for (int u = c; u < 768; u += G) { attnA_unit(a, u, lds); __syncthreads(); }
;         }
;     } else if (sub == 2) {
.LBB0_284:
	s_setprio 0
	v_readlane_b32 s4, v255, 19
	v_readlane_b32 s90, v255, 13
	v_readlane_b32 s8, v255, 23
	v_readlane_b32 s9, v255, 24
	s_mov_b32 s58, 0x55555555
	v_readlane_b32 s96, v255, 15
	v_readlane_b32 s91, v255, 14
	v_readlane_b32 s5, v255, 20
	v_readlane_b32 s6, v255, 21
	v_readlane_b32 s7, v255, 22
	s_mov_b64 s[76:77], s[8:9]
	v_readlane_b32 s92, v254, 21
	s_mov_b32 s64, 0x54442d18
	s_mov_b32 s66, 0x33145c00
	s_mov_b32 s59, 0xbfc55555
	v_readlane_b32 s62, v255, 17
	s_mov_b32 s96, s90
	v_readlane_b32 s82, v255, 10
	v_readlane_b32 s84, v255, 8
	v_readlane_b32 s88, v255, 6
	v_readlane_b32 s90, v255, 4
	v_readlane_b32 s94, v255, 2
	s_mov_b64 s[0:1], 0
	v_readlane_b32 s60, v254, 20
	v_readlane_b32 s10, v255, 25
	v_readlane_b32 s11, v255, 26
	s_mov_b64 s[74:75], s[6:7]
	s_mov_b64 s[72:73], s[4:5]
	v_readlane_b32 s93, v254, 22
	s_mov_b32 s65, 0xbff921fb
	s_mov_b32 s67, 0xbc91a626
	s_movk_i32 s57, 0x5800
	s_movk_i32 s61, 0xb00
	s_mov_b32 s31, 0xb00000
	s_mov_b32 s33, 0x800000
	s_mov_b32 s41, 0xda000000
	s_mov_b32 s71, 0xffff
	s_brev_b32 s36, 1
	s_movk_i32 s37, 0x1f8
	s_movk_i32 s38, 0x84
	s_movk_i32 s39, 0x2800
	s_brev_b32 s40, 18
	s_mov_b32 s48, 0x3c439041
	s_mov_b32 s49, 0xdb629599
	s_mov_b32 s50, 0xf534ddc0
	s_mov_b32 s51, 0xfc2757d1
	s_mov_b32 s52, 0x4e441529
	s_mov_b64 s[28:29], 0x4000
	s_mov_b64 s[12:13], 0x2000
	v_readlane_b32 s63, v255, 18
	v_readlane_b32 s97, v255, 16
	v_readlane_b32 s87, v255, 12
	v_readlane_b32 s83, v255, 11
	v_readlane_b32 s85, v255, 9
	v_readlane_b32 s89, v255, 7
	v_readlane_b32 s91, v255, 5
	v_readlane_b32 s95, v255, 3
	v_readlane_b32 s59, v255, 1
